# attn_t0 wave reductions via DPP/permlane instead of LDS shuffles
# speedup vs baseline: 1.0038x; 1.0038x over previous
.LBB0_351:
	s_or_b64 exec, exec, s[6:7]
	s_addk_i32 s0, 0x800
	s_ashr_i32 s1, s0, 31
	s_lshl_b64 s[0:1], s[0:1], 2
	s_add_u32 s0, s8, s0
	v_or_b32_e32 v4, s10, v233
	s_addc_u32 s1, s9, s1
	v_lshlrev_b32_e32 v4, 2, v4
	global_load_dword v4, v4, s[0:1]
	s_ashr_i32 s44, s43, 2
	s_add_i32 s0, s44, 1
	s_waitcnt vmcnt(0)
	v_max_f32_dpp v2, v2, v2 quad_perm:[1,0,3,2] row_mask:0xf bank_mask:0xf
	v_max_f32_dpp v3, v3, v3 quad_perm:[1,0,3,2] row_mask:0xf bank_mask:0xf
	v_min_f32_dpp v4, v4, v4 quad_perm:[1,0,3,2] row_mask:0xf bank_mask:0xf
	v_max_f32_dpp v2, v2, v2 quad_perm:[2,3,0,1] row_mask:0xf bank_mask:0xf
	v_max_f32_dpp v3, v3, v3 quad_perm:[2,3,0,1] row_mask:0xf bank_mask:0xf
	v_min_f32_dpp v4, v4, v4 quad_perm:[2,3,0,1] row_mask:0xf bank_mask:0xf
	v_max_f32_dpp v2, v2, v2 row_half_mirror row_mask:0xf bank_mask:0xf
	v_max_f32_dpp v3, v3, v3 row_half_mirror row_mask:0xf bank_mask:0xf
	v_min_f32_dpp v4, v4, v4 row_half_mirror row_mask:0xf bank_mask:0xf
	v_max_f32_dpp v2, v2, v2 row_mirror row_mask:0xf bank_mask:0xf
	v_max_f32_dpp v3, v3, v3 row_mirror row_mask:0xf bank_mask:0xf
	v_min_f32_dpp v4, v4, v4 row_mirror row_mask:0xf bank_mask:0xf
	v_mov_b32_e32 v5, v2
	v_mov_b32_e32 v6, v3
	v_mov_b32_e32 v7, v4
	s_nop 0
	v_permlane16_swap_b32_e32 v2, v5
	v_permlane16_swap_b32_e32 v3, v6
	v_permlane16_swap_b32_e32 v4, v7
	v_max_f32_e32 v2, v2, v5
	v_max_f32_e32 v3, v3, v6
	v_min_f32_e32 v4, v4, v7
	v_mov_b32_e32 v5, v2
	v_mov_b32_e32 v6, v3
	v_mov_b32_e32 v7, v4
	s_nop 0
	v_permlane32_swap_b32_e32 v2, v5
	v_permlane32_swap_b32_e32 v3, v6
	v_permlane32_swap_b32_e32 v4, v7
	v_min_f32_e32 v4, v4, v7
	v_max_f32_e32 v7, v3, v6
	v_max_f32_e32 v6, v2, v5
	v_mov_b32_e32 v3, v4
	v_cvt_f32_i32_e32 v4, s0
	s_mov_b32 s0, 0xc2fc0000
	v_mul_f32_e32 v2, -2.0, v4
	v_cmp_gt_f32_e32 vcc, s0, v2
	s_and_b64 s[0:1], vcc, exec
	s_cselect_b32 s0, 0xffffffc0, 0
	v_cndmask_b32_e32 v5, 0, v1, vcc
	v_fmac_f32_e32 v5, -2.0, v4
	v_exp_f32_e32 v4, v5
	v_cmp_gt_f32_e32 vcc, s27, v7
	s_lshl_b32 s47, s30, 8
	v_ldexp_f32 v4, v4, s0
	v_mul_f32_e32 v8, 0xbfb8aa3b, v4
	v_mul_f32_e32 v4, 0x4f800000, v7
	v_cndmask_b32_e32 v4, v7, v4, vcc
	v_sqrt_f32_e32 v5, v4
	s_nop 0
	v_add_u32_e32 v7, -1, v5
	v_fma_f32 v9, -v7, v5, v4
	v_cmp_ge_f32_e64 s[0:1], 0, v9
	v_add_u32_e32 v9, 1, v5
	s_nop 0
	v_cndmask_b32_e64 v7, v5, v7, s[0:1]
	v_fma_f32 v5, -v9, v5, v4
	v_cmp_lt_f32_e64 s[0:1], 0, v5
	s_nop 1
	v_cndmask_b32_e64 v5, v7, v9, s[0:1]
	v_mul_f32_e32 v7, 0x37800000, v5
	v_cndmask_b32_e32 v5, v5, v7, vcc
	v_cmp_class_f32_e32 vcc, v4, v234
	s_nop 1
	v_cndmask_b32_e32 v4, v5, v4, vcc
	v_mul_f32_e32 v209, 0x3f8147ae, v4
	v_cmp_gt_f32_e32 vcc, s27, v6
	v_mul_f32_e32 v4, 0x4f800000, v6
	s_nop 0
	v_cndmask_b32_e32 v4, v6, v4, vcc
	v_sqrt_f32_e32 v5, v4
	s_nop 0
	v_add_u32_e32 v6, -1, v5
	v_fma_f32 v7, -v6, v5, v4
	v_cmp_ge_f32_e64 s[0:1], 0, v7
	v_add_u32_e32 v7, 1, v5
	s_nop 0
	v_cndmask_b32_e64 v6, v5, v6, s[0:1]
	v_fma_f32 v5, -v7, v5, v4
	v_cmp_lt_f32_e64 s[0:1], 0, v5
	s_nop 1
	v_cndmask_b32_e64 v5, v6, v7, s[0:1]
	v_mul_f32_e32 v6, 0x37800000, v5
	v_cndmask_b32_e32 v5, v5, v6, vcc
	v_cmp_class_f32_e32 vcc, v4, v234
	s_nop 1
	v_cndmask_b32_e32 v5, v5, v4, vcc
	v_and_b32_e32 v4, 0x7fffffff, v3
	v_pk_mul_f32 v[4:5], v[4:5], v[208:209]
	s_nop 0
	v_sub_f32_e32 v3, v5, v3
	v_add_f32_e32 v3, v4, v3
	v_add_f32_e32 v3, 0x42420000, v3
	v_div_scale_f32 v4, s[0:1], v8, v8, v3
	v_rcp_f32_e32 v5, v4
	s_nop 0
	v_fma_f32 v6, -v4, v5, 1.0
	v_fmac_f32_e32 v5, v6, v5
	v_div_scale_f32 v6, vcc, v3, v8, v3
	v_mul_f32_e32 v7, v6, v5
	v_fma_f32 v9, -v4, v7, v6
	v_fmac_f32_e32 v7, v9, v5
	v_fma_f32 v4, -v4, v7, v6
	v_div_fmas_f32 v4, v4, v5, v7
	v_div_fixup_f32 v3, v4, v8, v3
	v_cvt_f32_u32_e32 v4, s47
	v_add_f32_e32 v3, v4, v3
	v_cmp_lt_f32_e32 vcc, 0, v3
	v_mul_f32_e32 v3, 0x3c800000, v3
	v_cvt_i32_f32_e32 v3, v3
	v_and_b32_e32 v3, -2, v3
	v_min_i32_e32 v3, s10, v3
	v_cndmask_b32_e32 v3, 0, v3, vcc
	s_nop 0
	v_readfirstlane_b32 s0, v3
	s_and_saveexec_b64 s[6:7], s[14:15]
	s_cbranch_execz .LBB0_355
	s_mov_b64 s[30:31], exec
	v_mbcnt_lo_u32_b32 v3, s30, 0
	v_mbcnt_hi_u32_b32 v3, s31, v3
	v_cmp_eq_u32_e32 vcc, 0, v3
	s_and_saveexec_b64 s[28:29], vcc
	s_cbranch_execz .LBB0_354
	s_bcnt1_i32_b64 s1, s[30:31]
	v_mov_b32_e32 v252, s1
	global_atomic_add v252, v207, v252, s[68:69] sc0
